# speedup vs baseline: 1.0003x; 1.0003x over previous
; DEV int bidx() { int b = __builtin_amdgcn_readfirstlane(blockIdx.x); asm volatile("" : "+s"(b)); return b; }
; DEV int gdim() { int g = __builtin_amdgcn_readfirstlane(gridDim.x); asm volatile("" : "+s"(g)); return g; }
; DEV void gdn_prep_item(const Params& p, int layer, int item, char* smem) {
;     ...
; #pragma unroll
;   for (int i = 0; i < 4; i++) {
;     const int cc = tid + i * 256, row = cc >> 4, kc = cc & 15;
;     *(uint4*)(ip.w + ((((row >> 4) * 4 + (kc >> 2)) * 64 + (kc & 3) * 16 + (row & 15)) << 3)) = *(const uint4*)(sVv + row * 136 + kc * 8);
;   }
;   __syncthreads();
; __global__ void __launch_bounds__(256, 2) fwd_megakernel(Params p) {
;     ...
;     for (int item = bidx(); item < 528 * 8; item += gdim()) gdn_prep_item(p, layer, item, smem);
.LBB0_1002:
	s_or_b64 exec, exec, s[0:1]
	s_waitcnt lgkmcnt(0)
	s_barrier
	ds_read_b128 v[2:5], v8 offset:34816
	v_readlane_b32 s0, v255, 41
	v_readlane_b32 s1, v255, 42
	s_nop 1
	v_lshl_add_u64 v[6:7], v[10:11], 1, s[0:1]
	s_waitcnt lgkmcnt(0)
	global_store_dwordx4 v[6:7], v[2:5], off
	ds_read_b128 v[2:5], v12 offset:34816
	v_lshl_add_u64 v[6:7], v[16:17], 1, s[0:1]
	s_waitcnt lgkmcnt(0)
	global_store_dwordx4 v[6:7], v[2:5], off
	ds_read_b128 v[2:5], v14 offset:34816
	v_lshl_add_u64 v[6:7], v[20:21], 1, s[0:1]
	s_waitcnt lgkmcnt(0)
	global_store_dwordx4 v[6:7], v[2:5], off
	ds_read_b128 v[2:5], v18 offset:34816
	v_lshl_add_u64 v[6:7], v[22:23], 1, s[0:1]
	v_readfirstlane_b32 s0, v198
	s_waitcnt lgkmcnt(0)
	global_store_dwordx4 v[6:7], v[2:5], off
	s_barrier
	s_mov_b32 s20, s101
	s_add_i32 s20, s0, s20
	s_cmpk_gt_i32 s20, 0x107f
	s_cbranch_scc1 .LBB0_1100
.LBB0_1003:
	s_mov_b32 s101, s20
	s_cmpk_gt_i32 s20, 0xfff
	s_cbranch_scc1 .Lpp_id
	s_and_b32 s0, s20, 7
	s_lshl_b32 s0, s0, 3
	s_bfe_u32 s1, s20, 0x30006
	s_add_i32 s0, s0, s1
	s_lshl_b32 s0, s0, 3
	s_bfe_u32 s1, s20, 0x30003
	s_add_i32 s0, s0, s1
	s_andn2_b32 s20, s20, 0x1ff
	s_add_i32 s20, s20, s0
